# h3 A blocks: the eight ds_read_b128 of a block issued together with counted waits instead of one pair per lgkmcnt(0), on top of v9
# speedup vs baseline: 1.0051x; 1.0027x over previous
.LBB0_379:
	v_add_u32_e32 v12, s11, v139
	ds_read_b128 v[0:3], v12
	v_add_u32_e32 v13, s12, v139
	ds_read_b128 v[4:7], v13
	ds_read_b128 v[180:183], v12 offset:64
	ds_read_b128 v[184:187], v13 offset:64
	ds_read_b128 v[188:191], v12 offset:128
	ds_read_b128 v[192:195], v13 offset:128
	ds_read_b128 v[196:199], v12 offset:192
	ds_read_b128 v[200:203], v13 offset:192
	s_cmp_eq_u32 s10, s9
	s_cselect_b64 s[0:1], -1, 0
	s_lshl_b32 s12, s10, 4
	s_and_b64 s[10:11], s[0:1], s[44:45]
	s_add_i32 s5, s5, 0x8800
	s_waitcnt lgkmcnt(6)
	v_mfma_f32_16x16x32_bf16 v[0:3], v[0:3], v[4:7], 0
	s_waitcnt lgkmcnt(4)
	v_mfma_f32_16x16x32_bf16 v[0:3], v[180:183], v[184:187], v[0:3]
	s_waitcnt lgkmcnt(2)
	v_mfma_f32_16x16x32_bf16 v[0:3], v[188:191], v[192:195], v[0:3]
	s_waitcnt lgkmcnt(0)
	v_mfma_f32_16x16x32_bf16 v[0:3], v[196:199], v[200:203], v[0:3]
	v_lshl_add_u32 v4, s9, 5, v134
	v_or_b32_e32 v5, s12, v135
	s_movk_i32 s9, 0x90
	s_nop 4
	v_cvt_pk_bf16_f32 v0, v0, s0
	v_cndmask_b32_e64 v0, v0, 0, s[10:11]
	v_mad_u64_u32 v[6:7], s[10:11], v5, s9, v[4:5]
	ds_write_b16 v6, v0
	s_and_b64 s[10:11], s[0:1], s[46:47]
	v_cvt_pk_bf16_f32 v0, v1, s0
	v_cndmask_b32_e64 v5, v0, 0, s[10:11]
	v_or_b32_e32 v0, s12, v136
	v_mad_u64_u32 v[0:1], s[10:11], v0, s9, v[4:5]
	ds_write_b16 v0, v5
	s_and_b64 s[10:11], s[0:1], s[48:49]
	v_cvt_pk_bf16_f32 v0, v2, s0
	v_cndmask_b32_e64 v2, v0, 0, s[10:11]
	v_or_b32_e32 v0, s12, v137
	v_mad_u64_u32 v[0:1], s[10:11], v0, s9, v[4:5]
	s_and_b64 s[0:1], s[0:1], s[50:51]
	ds_write_b16 v0, v2
	v_cvt_pk_bf16_f32 v0, v3, s0
	v_cndmask_b32_e64 v2, v0, 0, s[0:1]
	v_or_b32_e32 v0, s12, v138
	v_mad_u64_u32 v[0:1], s[0:1], v0, s9, v[4:5]
	s_add_i32 s0, s8, 8
	s_cmp_lt_i32 s8, 2
	s_mov_b32 s8, s0
	ds_write_b16 v0, v2
	s_cbranch_scc0 .LBB0_300
